# GEMM K-loop LDS-DMA loads in scalar-base + 32-bit VGPR-offset form (16 v_lshl_add_u64 per wave-iteration removed); plus phase-0 nt loads and gate_up item remap
# speedup vs baseline: 1.0125x; 1.0044x over previous
; #define PG8_STAGE(bufoff, gbase, voff) do { _Pragma("unroll") for (int _i = 0; _i < 2; ++_i) \
;         __builtin_amdgcn_global_load_lds((const unsigned*)((const char*)(gbase) + (voff)[_i]), (LAS unsigned*)(lds + (bufoff) + ldsw + _i * 8192), 16, 0, 0); } while (0)
; #define PG8_LDA(dst, b, h) do { _Pragma("unroll") for (int m = 0; m < 4; ++m) _Pragma("unroll") for (int k = 0; k < 2; ++k) dst[m][k] = *(const LAS bf16x8*)(lds + PG8_SA(b, h) + aoff + m * 2048 + k * 1024); } while (0)
; #define PG8_LDB(dst, b, h) do { _Pragma("unroll") for (int n = 0; n < 2; ++n) _Pragma("unroll") for (int k = 0; k < 2; ++k) dst[n][k] = *(const LAS bf16x8*)(lds + PG8_SB(b, h) + boff + n * 2048 + k * 1024); } while (0)
; #define PG8_MMA(ai, bj, At, Bt) do { __builtin_amdgcn_s_setprio(1); _Pragma("unroll") for (int m = 0; m < 4; ++m) _Pragma("unroll") for (int n = 0; n < 2; ++n) _Pragma("unroll") for (int k = 0; k < 2; ++k) \
;         acc[ai][bj][m][n] = __builtin_amdgcn_mfma_f32_16x16x32_bf16(Bt[n][k], At[m][k], acc[ai][bj][m][n], 0, 0, 0); __builtin_amdgcn_s_setprio(0); } while (0)
; #define PG8_WAIT_V(n) asm volatile("s_waitcnt vmcnt(" #n ")" ::: "memory")
; #define PG8_WAIT_L(n) asm volatile("s_waitcnt lgkmcnt(" #n ")" ::: "memory")
; #define PG8_BAR __builtin_amdgcn_s_barrier()
; #define PG8_SCHED __builtin_amdgcn_sched_barrier(0)
; __device__ __forceinline__ void gemm_phase(LAS unsigned char* lds, const GP p, const int tid) {
;     ...
;             PG8_LDB(B0, 0, 0); PG8_LDB(B1, 0, 1); PG8_SCHED; PG8_LDA(At, 0, 0); PG8_STAGE(PG8_SA(1, 1), a1 + hstep, voffA);
;             PG8_WAIT_V(8); PG8_WAIT_L(0); PG8_BAR; PG8_MMA(0, 0, At, B0); PG8_MMA(0, 1, At, B1); PG8_BAR; PG8_SCHED;
;             PG8_LDA(At, 0, 1); PG8_STAGE(PG8_SB(0, 0), b2, voffB); PG8_STAGE(PG8_SB(0, 1), b2 + hstep, voffB); PG8_STAGE(PG8_SA(0, 0), a2, voffA);
;             PG8_WAIT_V(8); PG8_WAIT_L(0); PG8_BAR; PG8_MMA(1, 0, At, B0); PG8_MMA(1, 1, At, B1); PG8_BAR; PG8_SCHED;
.LBB0_104:
	s_add_i32 s98, s98, 2
	s_add_u32 s43, s82, 0x80
	s_addc_u32 s99, s83, 0
	s_and_b64 s[86:87], s[84:85], exec
	s_cselect_b32 s87, s77, s99
	s_cselect_b32 s86, s76, s43
	s_add_i32 s43, 0, 0x10000
	s_and_b64 s[84:85], s[84:85], exec
	v_add_u32_e32 v142, s43, v165
	s_cselect_b32 s85, s79, s91
	s_cselect_b32 s84, s78, s81
	s_add_i32 s99, 0, 0x14000
	ds_read_b128 v[130:133], v142
	ds_read_b128 v[134:137], v142 offset:1024
	ds_read_b128 v[138:141], v142 offset:2048
	ds_read_b128 v[180:183], v142 offset:3072
	v_add_u32_e32 v142, s99, v165
	ds_read_b128 v[184:187], v142
	ds_read_b128 v[188:191], v142 offset:1024
	ds_read_b128 v[192:195], v142 offset:2048
	ds_read_b128 v[196:199], v142 offset:3072
	s_add_i32 m0, s53, 0xc000
	ds_read_b128 v[200:203], v167
	ds_read_b128 v[204:207], v167 offset:1024
	ds_read_b128 v[208:211], v167 offset:2048
	ds_read_b128 v[218:221], v167 offset:3072
	ds_read_b128 v[222:225], v167 offset:4096
	ds_read_b128 v[226:229], v167 offset:5120
	ds_read_b128 v[230:233], v167 offset:6144
	ds_read_b128 v[234:237], v167 offset:7168
	global_load_lds_dwordx4 v160, s[82:83]
	s_add_i32 m0, s53, 0xe000
	s_nop 0
	global_load_lds_dwordx4 v162, s[82:83]
	s_waitcnt vmcnt(8)
	s_waitcnt lgkmcnt(0)
	s_barrier
	s_setprio 1
	s_waitcnt lgkmcnt(0)
	v_mfma_f32_16x16x32_bf16 v[124:127], v[130:133], v[200:203], v[124:127]
	v_mfma_f32_16x16x32_bf16 v[120:123], v[138:141], v[200:203], v[120:123]
	v_mfma_f32_16x16x32_bf16 v[108:111], v[130:133], v[208:211], v[108:111]
	v_mfma_f32_16x16x32_bf16 v[104:107], v[138:141], v[208:211], v[104:107]
	v_mfma_f32_16x16x32_bf16 v[92:95], v[130:133], v[222:225], v[92:95]
	v_mfma_f32_16x16x32_bf16 v[88:91], v[138:141], v[222:225], v[88:91]
	v_mfma_f32_16x16x32_bf16 v[76:79], v[130:133], v[230:233], v[76:79]
	v_mfma_f32_16x16x32_bf16 v[72:75], v[138:141], v[230:233], v[72:75]
	v_mfma_f32_16x16x32_bf16 v[124:127], v[134:137], v[204:207], v[124:127]
	v_mfma_f32_16x16x32_bf16 v[120:123], v[180:183], v[204:207], v[120:123]
	v_mfma_f32_16x16x32_bf16 v[108:111], v[134:137], v[218:221], v[108:111]
	v_mfma_f32_16x16x32_bf16 v[104:107], v[180:183], v[218:221], v[104:107]
	v_mfma_f32_16x16x32_bf16 v[92:95], v[134:137], v[226:229], v[92:95]
	v_mfma_f32_16x16x32_bf16 v[88:91], v[180:183], v[226:229], v[88:91]
	v_mfma_f32_16x16x32_bf16 v[76:79], v[134:137], v[234:237], v[76:79]
	v_mfma_f32_16x16x32_bf16 v[72:75], v[180:183], v[234:237], v[72:75]
	s_setprio 0
	s_setprio 1
	v_mfma_f32_16x16x32_bf16 v[116:119], v[184:187], v[200:203], v[116:119]
	v_mfma_f32_16x16x32_bf16 v[112:115], v[192:195], v[200:203], v[112:115]
	v_mfma_f32_16x16x32_bf16 v[100:103], v[184:187], v[208:211], v[100:103]
	v_mfma_f32_16x16x32_bf16 v[96:99], v[192:195], v[208:211], v[96:99]
	v_mfma_f32_16x16x32_bf16 v[84:87], v[184:187], v[222:225], v[84:87]
	v_mfma_f32_16x16x32_bf16 v[80:83], v[192:195], v[222:225], v[80:83]
	v_mfma_f32_16x16x32_bf16 v[68:71], v[184:187], v[230:233], v[68:71]
	v_mfma_f32_16x16x32_bf16 v[64:67], v[192:195], v[230:233], v[64:67]
	v_mfma_f32_16x16x32_bf16 v[116:119], v[188:191], v[204:207], v[116:119]
	v_mfma_f32_16x16x32_bf16 v[112:115], v[196:199], v[204:207], v[112:115]
	v_mfma_f32_16x16x32_bf16 v[100:103], v[188:191], v[218:221], v[100:103]
	v_mfma_f32_16x16x32_bf16 v[96:99], v[196:199], v[218:221], v[96:99]
	v_mfma_f32_16x16x32_bf16 v[84:87], v[188:191], v[226:229], v[84:87]
	v_mfma_f32_16x16x32_bf16 v[80:83], v[196:199], v[226:229], v[80:83]
	v_mfma_f32_16x16x32_bf16 v[68:71], v[188:191], v[234:237], v[68:71]
	v_mfma_f32_16x16x32_bf16 v[64:67], v[196:199], v[234:237], v[64:67]
	s_setprio 0
	s_barrier
	s_add_i32 s43, s43, s52
	s_mov_b64 s[100:101], s[84:85]
	s_mov_b32 m0, s43
	ds_read_b128 v[200:203], v167 offset:16384
	ds_read_b128 v[204:207], v167 offset:17408
	ds_read_b128 v[208:211], v167 offset:18432
	ds_read_b128 v[218:221], v167 offset:19456
	ds_read_b128 v[222:225], v167 offset:20480
	ds_read_b128 v[226:229], v167 offset:21504
	ds_read_b128 v[230:233], v167 offset:22528
	ds_read_b128 v[234:237], v167 offset:23552
	global_load_lds_dwordx4 v148, s[84:85]
	s_add_i32 m0, s43, 0x2000
	s_add_i32 s43, s99, s52
	global_load_lds_dwordx4 v152, s[84:85]
	s_add_u32 s84, s84, s74
	s_addc_u32 s85, s85, 0
	s_mov_b32 m0, s43
	s_nop 0
	global_load_lds_dwordx4 v148, s[84:85]
	s_add_i32 m0, s43, 0x2000
	s_nop 0
	global_load_lds_dwordx4 v152, s[84:85]
	s_mov_b32 m0, s53
	s_nop 0
	global_load_lds_dwordx4 v146, s[86:87]
	s_mov_b32 m0, s54
	s_nop 0
	global_load_lds_dwordx4 v150, s[86:87]
	s_waitcnt vmcnt(8)
	s_waitcnt lgkmcnt(0)
	s_barrier
; #define PG8_STAGE(bufoff, gbase, voff) do { _Pragma("unroll") for (int _i = 0; _i < 2; ++_i) \
;         __builtin_amdgcn_global_load_lds((const unsigned*)((const char*)(gbase) + (voff)[_i]), (LAS unsigned*)(lds + (bufoff) + ldsw + _i * 8192), 16, 0, 0); } while (0)
; #define PG8_LDA(dst, b, h) do { _Pragma("unroll") for (int m = 0; m < 4; ++m) _Pragma("unroll") for (int k = 0; k < 2; ++k) dst[m][k] = *(const LAS bf16x8*)(lds + PG8_SA(b, h) + aoff + m * 2048 + k * 1024); } while (0)
; #define PG8_LDB(dst, b, h) do { _Pragma("unroll") for (int n = 0; n < 2; ++n) _Pragma("unroll") for (int k = 0; k < 2; ++k) dst[n][k] = *(const LAS bf16x8*)(lds + PG8_SB(b, h) + boff + n * 2048 + k * 1024); } while (0)
; #define PG8_MMA(ai, bj, At, Bt) do { __builtin_amdgcn_s_setprio(1); _Pragma("unroll") for (int m = 0; m < 4; ++m) _Pragma("unroll") for (int n = 0; n < 2; ++n) _Pragma("unroll") for (int k = 0; k < 2; ++k) \
;         acc[ai][bj][m][n] = __builtin_amdgcn_mfma_f32_16x16x32_bf16(Bt[n][k], At[m][k], acc[ai][bj][m][n], 0, 0, 0); __builtin_amdgcn_s_setprio(0); } while (0)
; #define PG8_WAIT_V(n) asm volatile("s_waitcnt vmcnt(" #n ")" ::: "memory")
; #define PG8_WAIT_L(n) asm volatile("s_waitcnt lgkmcnt(" #n ")" ::: "memory")
; #define PG8_BAR __builtin_amdgcn_s_barrier()
; #define PG8_SCHED __builtin_amdgcn_sched_barrier(0)
; __device__ __forceinline__ void gemm_phase(LAS unsigned char* lds, const GP p, const int tid) {
;     ...
;             PG8_WAIT_V(8); PG8_WAIT_L(0); PG8_BAR; PG8_MMA(1, 0, At, B0); PG8_MMA(1, 1, At, B1); PG8_BAR; PG8_SCHED;
;             PG8_LDB(B0, 1, 0); PG8_LDB(B1, 1, 1); PG8_SCHED; PG8_LDA(At, 1, 0); PG8_STAGE(PG8_SA(0, 1), a2 + hstep, voffA);
;             PG8_WAIT_V(8); PG8_WAIT_L(0); PG8_BAR; PG8_MMA(0, 0, At, B0); PG8_MMA(0, 1, At, B1); PG8_BAR; PG8_SCHED;
	s_setprio 1
	s_waitcnt lgkmcnt(0)
	v_mfma_f32_16x16x32_bf16 v[60:63], v[130:133], v[200:203], v[60:63]
	v_mfma_f32_16x16x32_bf16 v[56:59], v[138:141], v[200:203], v[56:59]
	v_mfma_f32_16x16x32_bf16 v[44:47], v[130:133], v[208:211], v[44:47]
	v_mfma_f32_16x16x32_bf16 v[40:43], v[138:141], v[208:211], v[40:43]
	v_mfma_f32_16x16x32_bf16 v[28:31], v[130:133], v[222:225], v[28:31]
	v_mfma_f32_16x16x32_bf16 v[24:27], v[138:141], v[222:225], v[24:27]
	v_mfma_f32_16x16x32_bf16 v[12:15], v[130:133], v[230:233], v[12:15]
	v_mfma_f32_16x16x32_bf16 v[8:11], v[138:141], v[230:233], v[8:11]
	v_mfma_f32_16x16x32_bf16 v[60:63], v[134:137], v[204:207], v[60:63]
	v_mfma_f32_16x16x32_bf16 v[56:59], v[180:183], v[204:207], v[56:59]
	v_mfma_f32_16x16x32_bf16 v[44:47], v[134:137], v[218:221], v[44:47]
	v_mfma_f32_16x16x32_bf16 v[40:43], v[180:183], v[218:221], v[40:43]
	v_mfma_f32_16x16x32_bf16 v[28:31], v[134:137], v[226:229], v[28:31]
	v_mfma_f32_16x16x32_bf16 v[24:27], v[180:183], v[226:229], v[24:27]
	v_mfma_f32_16x16x32_bf16 v[12:15], v[134:137], v[234:237], v[12:15]
	v_mfma_f32_16x16x32_bf16 v[8:11], v[180:183], v[234:237], v[8:11]
	s_setprio 0
	s_setprio 1
	v_mfma_f32_16x16x32_bf16 v[52:55], v[184:187], v[200:203], v[52:55]
	v_mfma_f32_16x16x32_bf16 v[48:51], v[192:195], v[200:203], v[48:51]
	v_mfma_f32_16x16x32_bf16 v[36:39], v[184:187], v[208:211], v[36:39]
	v_mfma_f32_16x16x32_bf16 v[32:35], v[192:195], v[208:211], v[32:35]
	v_mfma_f32_16x16x32_bf16 v[20:23], v[184:187], v[222:225], v[20:23]
	v_mfma_f32_16x16x32_bf16 v[16:19], v[192:195], v[222:225], v[16:19]
	v_mfma_f32_16x16x32_bf16 v[4:7], v[184:187], v[230:233], v[4:7]
	v_mfma_f32_16x16x32_bf16 v[0:3], v[192:195], v[230:233], v[0:3]
	v_mfma_f32_16x16x32_bf16 v[52:55], v[188:191], v[204:207], v[52:55]
	v_mfma_f32_16x16x32_bf16 v[48:51], v[196:199], v[204:207], v[48:51]
	v_mfma_f32_16x16x32_bf16 v[36:39], v[188:191], v[218:221], v[36:39]
	v_mfma_f32_16x16x32_bf16 v[32:35], v[196:199], v[218:221], v[32:35]
	v_mfma_f32_16x16x32_bf16 v[20:23], v[188:191], v[226:229], v[20:23]
	v_mfma_f32_16x16x32_bf16 v[16:19], v[196:199], v[226:229], v[16:19]
	v_mfma_f32_16x16x32_bf16 v[4:7], v[188:191], v[234:237], v[4:7]
	v_mfma_f32_16x16x32_bf16 v[0:3], v[196:199], v[234:237], v[0:3]
	s_setprio 0
	s_barrier
	s_add_i32 s43, 0, 0x18000
	v_add_u32_e32 v144, s43, v165
	s_add_i32 s99, 0, 0x1c000
	ds_read_b128 v[130:133], v144
	ds_read_b128 v[134:137], v144 offset:1024
	ds_read_b128 v[138:141], v144 offset:2048
	ds_read_b128 v[180:183], v144 offset:3072
	v_add_u32_e32 v144, s99, v165
	ds_read_b128 v[184:187], v144
	ds_read_b128 v[188:191], v144 offset:1024
	ds_read_b128 v[192:195], v144 offset:2048
	ds_read_b128 v[196:199], v144 offset:3072
	s_add_u32 s84, s86, s74
	s_addc_u32 s85, s87, 0
	s_mov_b32 m0, s55
	ds_read_b128 v[200:203], v167 offset:32768
	ds_read_b128 v[204:207], v167 offset:33792
	ds_read_b128 v[208:211], v167 offset:34816
	ds_read_b128 v[218:221], v167 offset:35840
	ds_read_b128 v[222:225], v167 offset:36864
	ds_read_b128 v[226:229], v167 offset:37888
	ds_read_b128 v[230:233], v167 offset:38912
	ds_read_b128 v[234:237], v167 offset:39936
	global_load_lds_dwordx4 v146, s[84:85]
	s_mov_b32 m0, s56
	s_nop 0
	global_load_lds_dwordx4 v150, s[84:85]
	s_waitcnt vmcnt(8)
	s_waitcnt lgkmcnt(0)
	s_barrier
	s_setprio 1
	s_waitcnt lgkmcnt(0)
	v_mfma_f32_16x16x32_bf16 v[124:127], v[130:133], v[200:203], v[124:127]
	v_mfma_f32_16x16x32_bf16 v[120:123], v[138:141], v[200:203], v[120:123]
	v_mfma_f32_16x16x32_bf16 v[108:111], v[130:133], v[208:211], v[108:111]
	v_mfma_f32_16x16x32_bf16 v[104:107], v[138:141], v[208:211], v[104:107]
	v_mfma_f32_16x16x32_bf16 v[92:95], v[130:133], v[222:225], v[92:95]
	v_mfma_f32_16x16x32_bf16 v[88:91], v[138:141], v[222:225], v[88:91]
	v_mfma_f32_16x16x32_bf16 v[76:79], v[130:133], v[230:233], v[76:79]
	v_mfma_f32_16x16x32_bf16 v[72:75], v[138:141], v[230:233], v[72:75]
	v_mfma_f32_16x16x32_bf16 v[124:127], v[134:137], v[204:207], v[124:127]
	v_mfma_f32_16x16x32_bf16 v[120:123], v[180:183], v[204:207], v[120:123]
	v_mfma_f32_16x16x32_bf16 v[108:111], v[134:137], v[218:221], v[108:111]
	v_mfma_f32_16x16x32_bf16 v[104:107], v[180:183], v[218:221], v[104:107]
	v_mfma_f32_16x16x32_bf16 v[92:95], v[134:137], v[226:229], v[92:95]
	v_mfma_f32_16x16x32_bf16 v[88:91], v[180:183], v[226:229], v[88:91]
	v_mfma_f32_16x16x32_bf16 v[76:79], v[134:137], v[234:237], v[76:79]
	v_mfma_f32_16x16x32_bf16 v[72:75], v[180:183], v[234:237], v[72:75]
	s_setprio 0
	s_setprio 1
	v_mfma_f32_16x16x32_bf16 v[116:119], v[184:187], v[200:203], v[116:119]
	v_mfma_f32_16x16x32_bf16 v[112:115], v[192:195], v[200:203], v[112:115]
	v_mfma_f32_16x16x32_bf16 v[100:103], v[184:187], v[208:211], v[100:103]
	v_mfma_f32_16x16x32_bf16 v[96:99], v[192:195], v[208:211], v[96:99]
	v_mfma_f32_16x16x32_bf16 v[84:87], v[184:187], v[222:225], v[84:87]
	v_mfma_f32_16x16x32_bf16 v[80:83], v[192:195], v[222:225], v[80:83]
	v_mfma_f32_16x16x32_bf16 v[68:71], v[184:187], v[230:233], v[68:71]
	v_mfma_f32_16x16x32_bf16 v[64:67], v[192:195], v[230:233], v[64:67]
	v_mfma_f32_16x16x32_bf16 v[116:119], v[188:191], v[204:207], v[116:119]
	v_mfma_f32_16x16x32_bf16 v[112:115], v[196:199], v[204:207], v[112:115]
	v_mfma_f32_16x16x32_bf16 v[100:103], v[188:191], v[218:221], v[100:103]
	v_mfma_f32_16x16x32_bf16 v[96:99], v[196:199], v[218:221], v[96:99]
	v_mfma_f32_16x16x32_bf16 v[84:87], v[188:191], v[226:229], v[84:87]
	v_mfma_f32_16x16x32_bf16 v[80:83], v[196:199], v[226:229], v[80:83]
	v_mfma_f32_16x16x32_bf16 v[68:71], v[188:191], v[234:237], v[68:71]
	v_mfma_f32_16x16x32_bf16 v[64:67], v[196:199], v[234:237], v[64:67]
	s_setprio 0
	s_barrier
; #define PG8_STAGE(bufoff, gbase, voff) do { _Pragma("unroll") for (int _i = 0; _i < 2; ++_i) \
;         __builtin_amdgcn_global_load_lds((const unsigned*)((const char*)(gbase) + (voff)[_i]), (LAS unsigned*)(lds + (bufoff) + ldsw + _i * 8192), 16, 0, 0); } while (0)
; #define PG8_LDA(dst, b, h) do { _Pragma("unroll") for (int m = 0; m < 4; ++m) _Pragma("unroll") for (int k = 0; k < 2; ++k) dst[m][k] = *(const LAS bf16x8*)(lds + PG8_SA(b, h) + aoff + m * 2048 + k * 1024); } while (0)
; #define PG8_MMA(ai, bj, At, Bt) do { __builtin_amdgcn_s_setprio(1); _Pragma("unroll") for (int m = 0; m < 4; ++m) _Pragma("unroll") for (int n = 0; n < 2; ++n) _Pragma("unroll") for (int k = 0; k < 2; ++k) \
;         acc[ai][bj][m][n] = __builtin_amdgcn_mfma_f32_16x16x32_bf16(Bt[n][k], At[m][k], acc[ai][bj][m][n], 0, 0, 0); __builtin_amdgcn_s_setprio(0); } while (0)
; #define PG8_WAIT_V(n) asm volatile("s_waitcnt vmcnt(" #n ")" ::: "memory")
; #define PG8_WAIT_L(n) asm volatile("s_waitcnt lgkmcnt(" #n ")" ::: "memory")
; #define PG8_BAR __builtin_amdgcn_s_barrier()
; #define PG8_SCHED __builtin_amdgcn_sched_barrier(0)
; __device__ __forceinline__ void gemm_phase(LAS unsigned char* lds, const GP p, const int tid) {
;     ...
;             PG8_LDA(At, 1, 1); PG8_STAGE(PG8_SB(1, 0), b3, voffB); PG8_STAGE(PG8_SB(1, 1), b3 + hstep, voffB); PG8_STAGE(PG8_SA(1, 0), a3, voffA);
;             PG8_WAIT_V(8); PG8_WAIT_L(0); PG8_BAR; PG8_MMA(1, 0, At, B0); PG8_MMA(1, 1, At, B1); PG8_BAR; PG8_SCHED;
	s_add_i32 s43, s43, s52
	s_add_u32 s100, s100, 0x80
	s_addc_u32 s101, s101, 0
	s_mov_b32 m0, s43
	ds_read_b128 v[200:203], v167 offset:49152
	ds_read_b128 v[204:207], v167 offset:50176
	ds_read_b128 v[208:211], v167 offset:51200
	ds_read_b128 v[218:221], v167 offset:52224
	ds_read_b128 v[222:225], v167 offset:53248
	ds_read_b128 v[226:229], v167 offset:54272
	ds_read_b128 v[230:233], v167 offset:55296
	ds_read_b128 v[234:237], v167 offset:56320
	global_load_lds_dwordx4 v148, s[100:101]
	s_add_i32 m0, s43, 0x2000
	s_add_i32 s43, s99, s52
	global_load_lds_dwordx4 v152, s[100:101]
	s_add_u32 s100, s100, s74
	s_addc_u32 s101, s101, 0
	s_mov_b32 m0, s43
	s_nop 0
	global_load_lds_dwordx4 v148, s[100:101]
	s_add_u32 s86, s86, 0x80
	s_addc_u32 s87, s87, 0
	s_add_i32 m0, s43, 0x2000
	s_nop 0
	global_load_lds_dwordx4 v152, s[100:101]
	s_mov_b32 m0, s57
	s_nop 0
	global_load_lds_dwordx4 v146, s[86:87]
	s_mov_b32 m0, s58
	s_nop 0
	global_load_lds_dwordx4 v150, s[86:87]
	s_waitcnt vmcnt(8)
	s_waitcnt lgkmcnt(0)
	s_barrier
	s_setprio 1
	s_waitcnt lgkmcnt(0)
	v_mfma_f32_16x16x32_bf16 v[60:63], v[130:133], v[200:203], v[60:63]
	v_mfma_f32_16x16x32_bf16 v[56:59], v[138:141], v[200:203], v[56:59]
	v_mfma_f32_16x16x32_bf16 v[44:47], v[130:133], v[208:211], v[44:47]
	v_mfma_f32_16x16x32_bf16 v[40:43], v[138:141], v[208:211], v[40:43]
	v_mfma_f32_16x16x32_bf16 v[28:31], v[130:133], v[222:225], v[28:31]
	v_mfma_f32_16x16x32_bf16 v[24:27], v[138:141], v[222:225], v[24:27]
	v_mfma_f32_16x16x32_bf16 v[12:15], v[130:133], v[230:233], v[12:15]
	v_mfma_f32_16x16x32_bf16 v[8:11], v[138:141], v[230:233], v[8:11]
	v_mfma_f32_16x16x32_bf16 v[60:63], v[134:137], v[204:207], v[60:63]
	v_mfma_f32_16x16x32_bf16 v[56:59], v[180:183], v[204:207], v[56:59]
	v_mfma_f32_16x16x32_bf16 v[44:47], v[134:137], v[218:221], v[44:47]
	v_mfma_f32_16x16x32_bf16 v[40:43], v[180:183], v[218:221], v[40:43]
	v_mfma_f32_16x16x32_bf16 v[28:31], v[134:137], v[226:229], v[28:31]
	v_mfma_f32_16x16x32_bf16 v[24:27], v[180:183], v[226:229], v[24:27]
	v_mfma_f32_16x16x32_bf16 v[12:15], v[134:137], v[234:237], v[12:15]
	v_mfma_f32_16x16x32_bf16 v[8:11], v[180:183], v[234:237], v[8:11]
	s_setprio 0
	s_setprio 1
	v_mfma_f32_16x16x32_bf16 v[52:55], v[184:187], v[200:203], v[52:55]
	v_mfma_f32_16x16x32_bf16 v[48:51], v[192:195], v[200:203], v[48:51]
	v_mfma_f32_16x16x32_bf16 v[36:39], v[184:187], v[208:211], v[36:39]
	v_mfma_f32_16x16x32_bf16 v[32:35], v[192:195], v[208:211], v[32:35]
	v_mfma_f32_16x16x32_bf16 v[20:23], v[184:187], v[222:225], v[20:23]
	v_mfma_f32_16x16x32_bf16 v[16:19], v[192:195], v[222:225], v[16:19]
	v_mfma_f32_16x16x32_bf16 v[4:7], v[184:187], v[230:233], v[4:7]
	v_mfma_f32_16x16x32_bf16 v[0:3], v[192:195], v[230:233], v[0:3]
	v_mfma_f32_16x16x32_bf16 v[52:55], v[188:191], v[204:207], v[52:55]
	v_mfma_f32_16x16x32_bf16 v[48:51], v[196:199], v[204:207], v[48:51]
	v_mfma_f32_16x16x32_bf16 v[36:39], v[188:191], v[218:221], v[36:39]
	v_mfma_f32_16x16x32_bf16 v[32:35], v[196:199], v[218:221], v[32:35]
	v_mfma_f32_16x16x32_bf16 v[20:23], v[188:191], v[226:229], v[20:23]
	v_mfma_f32_16x16x32_bf16 v[16:19], v[196:199], v[226:229], v[16:19]
	v_mfma_f32_16x16x32_bf16 v[4:7], v[188:191], v[234:237], v[4:7]
	v_mfma_f32_16x16x32_bf16 v[0:3], v[196:199], v[234:237], v[0:3]
	s_setprio 0
	s_barrier
	s_add_u32 s82, s82, 0x100
	s_addc_u32 s83, s83, 0
	s_add_u32 s81, s81, 0x100
	s_addc_u32 s91, s91, 0
	s_cmp_ge_u32 s98, s60
	s_cbranch_scc1 .LBB0_107
